# retention scan loop: ds_read2_b64 split into 2x ds_read_b64 (conflict-free 64-bank reads), lgkmcnt recounted
# speedup vs baseline: 1.0170x; 1.0170x over previous
.LBB0_1370:
	s_add_i32 s1, s57, -1
	s_waitcnt vmcnt(7)
	ds_write_b128 v175, v[72:75]
	ds_write_b128 v175, v[68:71] offset:8704
	ds_write_b128 v175, v[64:67] offset:17408
	v_cndmask_b32_e32 v65, v180, v173, vcc
	v_xor_b32_e32 v66, 0xffffffef, v173
	v_xor_b32_e32 v70, 0xffffffcf, v173
	s_min_u32 s18, s1, s0
	v_add_u32_e32 v69, 48, v173
	v_xor_b32_e32 v67, 0xffffffdf, v173
	v_add_u32_e32 v71, s55, v66
	v_add_u32_e32 v66, s56, v65
	v_add_u32_e32 v70, s55, v70
	v_lshl_add_u32 v73, s18, 5, v174
	v_add_u32_e32 v64, 16, v173
	v_add_u32_e32 v68, 32, v173
	v_add_u32_e32 v65, s55, v67
	v_ashrrev_i32_e32 v67, 31, v66
	v_cndmask_b32_e32 v69, v70, v69, vcc
	v_xad_u32 v70, v73, -1, s55
	v_cndmask_b32_e32 v71, v71, v64, vcc
	v_cndmask_b32_e32 v68, v65, v68, vcc
	v_lshlrev_b64 v[64:65], 11, v[66:67]
	v_cndmask_b32_e32 v67, v70, v73, vcc
	s_min_u32 s42, s57, s0
	v_lshl_add_u64 v[242:243], v[170:171], 0, v[64:65]
	v_add_u32_e32 v64, s56, v67
	v_lshl_add_u32 v72, s42, 5, v174
	v_ashrrev_i32_e32 v65, 31, v64
	v_cvt_pk_bf16_f32 v60, v44, v45
	v_cvt_pk_bf16_f32 v61, v46, v47
	v_cvt_pk_bf16_f32 v62, v40, v41
	v_cvt_pk_bf16_f32 v63, v42, v43
	v_xad_u32 v74, v72, -1, s55
	v_lshlrev_b64 v[64:65], 13, v[64:65]
	v_cndmask_b32_e32 v66, v74, v72, vcc
	v_or_b32_e32 v64, v64, v181
	v_add_u32_e32 v238, s56, v68
	v_add_u32_e32 v240, s56, v69
	v_add_u32_e32 v244, s56, v66
	v_lshl_add_u64 v[66:67], s[36:37], 0, v[64:65]
	v_lshl_add_u64 v[68:69], s[38:39], 0, v[64:65]
	v_lshl_add_u64 v[64:65], s[40:41], 0, v[64:65]
	v_add_u32_e32 v0, 0x1000, v178
	v_add_u32_e32 v1, 0x2000, v179
	v_add_u32_e32 v182, 0x3000, v179
	v_add_u32_e32 v236, s56, v71
	global_load_dwordx4 v[72:75], v[66:67], off
	s_nop 0
	global_load_dwordx4 v[68:71], v[68:69], off
	s_nop 0
	global_load_dwordx4 v[64:67], v[64:65], off
	s_waitcnt lgkmcnt(0)
	s_barrier
	ds_read_b64 v[188:189], v178
	ds_read_b64 v[190:191], v178 offset:32
	ds_read_b64 v[192:193], v0 offset:256
	ds_read_b64 v[194:195], v0 offset:288
	ds_read_b64 v[196:197], v0 offset:320
	ds_read_b64 v[198:199], v0 offset:352
	ds_read_b64 v[200:201], v1 offset:512
	ds_read_b64 v[202:203], v1 offset:544
	ds_read_b64 v[204:205], v182 offset:768
	ds_read_b64 v[206:207], v182 offset:800
	ds_read_b64_tr_b16 v[210:211], v176 offset:13056
	ds_read_b64_tr_b16 v[212:213], v177 offset:17408
	ds_read_b64_tr_b16 v[214:215], v177 offset:21760
	ds_read_b64_tr_b16 v[208:209], v176 offset:8704
	ds_read_b64_tr_b16 v[216:217], v176 offset:8736
	ds_read_b64_tr_b16 v[220:221], v176 offset:8768
	ds_read_b64_tr_b16 v[222:223], v176 offset:13120
	ds_read_b64_tr_b16 v[218:219], v176 offset:13088
	ds_read_b64_tr_b16 v[230:231], v176 offset:8928
	s_waitcnt lgkmcnt(7)
	v_lshlrev_b32_e32 v232, 16, v212
	v_and_b32_e32 v233, 0xffff0000, v212
	v_lshlrev_b32_e32 v234, 16, v213
	v_and_b32_e32 v235, 0xffff0000, v213
	s_waitcnt lgkmcnt(6)
	v_lshlrev_b32_e32 v246, 16, v214
	v_and_b32_e32 v247, 0xffff0000, v214
	v_lshlrev_b32_e32 v248, 16, v215
	v_and_b32_e32 v249, 0xffff0000, v215
	v_mov_b32_e32 v159, v158
	v_mfma_f32_16x16x32_bf16 v[226:229], v[60:63], v[192:195], 0
	v_mul_f32_e64 v232, v150, v232
	v_mul_f32_e64 v233, v151, v233
	v_pk_mul_f32 v[234:235], v[152:153], v[234:235]
	v_pk_mul_f32 v[44:45], v[164:165], v[44:45]
	v_mfma_f32_16x16x32_bf16 v[60:63], v[60:63], v[188:191], 0
	v_mul_f32_e64 v46, v158, v46
	v_mul_f32_e64 v47, v159, v47
	v_pk_mul_f32 v[40:41], v[164:165], v[40:41]
	v_pk_mul_f32 v[42:43], v[158:159], v[42:43]
	v_mfma_f32_16x16x32_bf16 v[188:191], v[200:203], v[188:191], 0
	v_cvt_pk_bf16_f32 v52, v36, v37
	v_cvt_pk_bf16_f32 v53, v38, v39
	v_cvt_pk_bf16_f32 v54, v32, v33
	v_mfma_f32_16x16x32_bf16 v[200:203], v[200:203], v[192:195], 0
	v_cvt_pk_bf16_f32 v55, v34, v35
	v_cvt_pk_bf16_f32 v56, v28, v29
	v_cvt_pk_bf16_f32 v57, v30, v31
	v_mfma_f32_16x16x32_bf16 v[192:195], v[204:207], v[192:195], 0
	v_mul_f32_e64 v206, v154, v246
	v_mul_f32_e64 v207, v155, v247
	v_pk_mul_f32 v[246:247], v[156:157], v[248:249]
	v_cvt_pk_bf16_f32 v204, v232, v233
	v_cvt_pk_bf16_f32 v205, v234, v235
	v_cvt_pk_bf16_f32 v206, v206, v207
	v_cvt_pk_bf16_f32 v207, v246, v247
	v_pk_mul_f32 v[36:37], v[164:165], v[36:37]
	v_pk_mul_f32 v[32:33], v[164:165], v[32:33]
	s_waitcnt lgkmcnt(5)
	v_mfma_f32_16x16x32_bf16 v[44:47], v[208:211], v[204:207], v[44:47]
	ds_read_b64_tr_b16 v[210:211], v176 offset:13152
	ds_read_b64_tr_b16 v[208:209], v176 offset:8800
	ds_read_b64_tr_b16 v[232:233], v176 offset:8832
	v_pk_mul_f32 v[28:29], v[164:165], v[28:29]
	v_pk_mul_f32 v[38:39], v[158:159], v[38:39]
	s_waitcnt lgkmcnt(4)
	v_mfma_f32_16x16x32_bf16 v[40:43], v[216:219], v[204:207], v[40:43]
	ds_read_b64_tr_b16 v[216:217], v176 offset:8864
	ds_read_b64_tr_b16 v[234:235], v176 offset:13184
	ds_read_b64_tr_b16 v[218:219], v176 offset:13216
	v_pk_mul_f32 v[34:35], v[158:159], v[34:35]
	v_pk_mul_f32 v[30:31], v[158:159], v[30:31]
	v_mfma_f32_16x16x32_bf16 v[36:39], v[220:223], v[204:207], v[36:39]
	v_ashrrev_i32_e32 v245, 31, v244
	v_ashrrev_i32_e32 v237, 31, v236
	v_cvt_pk_bf16_f32 v58, v24, v25
	s_waitcnt lgkmcnt(4)
	v_mfma_f32_16x16x32_bf16 v[32:35], v[208:211], v[204:207], v[32:35]
	ds_read_b64_tr_b16 v[208:209], v176 offset:8896
	ds_read_b64_tr_b16 v[210:211], v176 offset:13248
	v_cvt_pk_bf16_f32 v59, v26, v27
	s_waitcnt lgkmcnt(3)
	v_mfma_f32_16x16x32_bf16 v[220:223], v[232:235], v[204:207], v[28:31]
	ds_read_b64_tr_b16 v[232:233], v176 offset:13280
	v_cvt_pk_bf16_f32 v48, v20, v21
	v_cvt_pk_bf16_f32 v49, v22, v23
	v_lshlrev_b64 v[28:29], 13, v[244:245]
	v_cvt_pk_bf16_f32 v50, v16, v17
	v_cvt_pk_bf16_f32 v51, v18, v19
	v_pk_mul_f32 v[24:25], v[164:165], v[24:25]
	v_pk_mul_f32 v[20:21], v[164:165], v[20:21]
	v_pk_mul_f32 v[16:17], v[164:165], v[16:17]
	v_pk_mul_f32 v[26:27], v[158:159], v[26:27]
	v_pk_mul_f32 v[22:23], v[158:159], v[22:23]
	v_pk_mul_f32 v[18:19], v[158:159], v[18:19]
	v_ashrrev_i32_e32 v239, 31, v238
	v_ashrrev_i32_e32 v241, 31, v240
	v_lshlrev_b64 v[236:237], 11, v[236:237]
	v_or_b32_e32 v28, v28, v181
	v_lshlrev_b64 v[246:247], 11, v[238:239]
	v_lshlrev_b64 v[248:249], 11, v[240:241]
	s_waitcnt lgkmcnt(3)
	v_mfma_f32_16x16x32_bf16 v[216:219], v[216:219], v[204:207], v[24:27]
	v_lshl_add_u64 v[234:235], v[170:171], 0, v[236:237]
	v_lshl_add_u64 v[236:237], s[36:37], 0, v[28:29]
	v_lshl_add_u64 v[238:239], s[38:39], 0, v[28:29]
	s_waitcnt lgkmcnt(1)
	v_mfma_f32_16x16x32_bf16 v[208:211], v[208:211], v[204:207], v[20:23]
	ds_read_b64 v[24:25], v1 offset:576
	ds_read_b64 v[26:27], v1 offset:608
	v_lshl_add_u64 v[240:241], s[40:41], 0, v[28:29]
	ds_read_b64 v[28:29], v182 offset:832
	ds_read_b64 v[30:31], v182 offset:864
	s_waitcnt lgkmcnt(4)
	v_mfma_f32_16x16x32_bf16 v[204:207], v[230:233], v[204:207], v[16:19]
	v_mov_b32_e32 v3, v2
	v_add_u32_e32 v183, 0x6000, v178
	v_add_u32_e32 v184, 0x7000, v178
	ds_read_b64 v[16:17], v178 offset:64
	ds_read_b64 v[18:19], v178 offset:96
	v_mfma_f32_16x16x32_bf16 v[226:229], v[52:55], v[196:199], v[226:229]
	v_add_u32_e32 v185, 0x8800, v179
	v_add_u32_e32 v186, 0x9800, v179
	s_add_i32 s57, s57, 2
	s_waitcnt lgkmcnt(0)
	v_mfma_f32_16x16x32_bf16 v[20:23], v[52:55], v[16:19], v[60:63]
	ds_read_b64 v[52:53], v0 offset:384
	ds_read_b64 v[54:55], v0 offset:416
	s_nop 1
	ds_read_b64 v[60:61], v178 offset:128
	ds_read_b64 v[62:63], v178 offset:160
	v_add_u32_e32 v173, 64, v173
	v_subrev_u32_e32 v180, 64, v180
	v_mfma_f32_16x16x32_bf16 v[16:19], v[24:27], v[16:19], v[188:191]
	s_cmp_ge_u32 s1, s58
	v_mfma_f32_16x16x32_bf16 v[24:27], v[24:27], v[196:199], v[200:203]
	v_mfma_f32_16x16x32_bf16 v[28:31], v[28:31], v[196:199], v[192:195]
	s_nop 2
	ds_read_b64 v[192:193], v1 offset:640
	ds_read_b64 v[194:195], v1 offset:672
	ds_read_b64 v[196:197], v178 offset:192
	ds_read_b64 v[198:199], v178 offset:224
	ds_read_b64 v[200:201], v0 offset:448
	ds_read_b64 v[202:203], v0 offset:480
	s_waitcnt lgkmcnt(8)
	v_mfma_f32_16x16x32_bf16 v[188:191], v[56:59], v[52:55], v[226:229]
	s_waitcnt lgkmcnt(6)
	v_mfma_f32_16x16x32_bf16 v[20:23], v[56:59], v[60:63], v[20:23]
	ds_read_b64 v[56:57], v182 offset:896
	ds_read_b64 v[58:59], v182 offset:928
	ds_read_b64 v[226:227], v1 offset:704
	ds_read_b64 v[228:229], v1 offset:736
	ds_read_b64 v[230:231], v182 offset:960
	ds_read_b64 v[232:233], v182 offset:992
	s_waitcnt vmcnt(5)
	ds_write_b128 v175, v[12:15] offset:26112
	ds_write_b128 v175, v[8:11] offset:34816
	ds_write_b128 v175, v[4:7] offset:43520
	s_waitcnt lgkmcnt(13)
	v_mfma_f32_16x16x32_bf16 v[16:19], v[192:195], v[60:63], v[16:19]
	v_mfma_f32_16x16x32_bf16 v[4:7], v[192:195], v[52:55], v[24:27]
	s_waitcnt lgkmcnt(7)
	v_mfma_f32_16x16x32_bf16 v[8:11], v[56:59], v[52:55], v[28:31]
	s_nop 0
	v_cvt_pk_bf16_f32 v24, v44, v45
	v_cvt_pk_bf16_f32 v25, v46, v47
	v_cvt_pk_bf16_f32 v26, v40, v41
	s_waitcnt lgkmcnt(5)
	v_mfma_f32_16x16x32_bf16 v[16:19], v[226:229], v[196:199], v[16:19]
	v_mul_f32_e64 v28, v164, v44
	v_mul_f32_e64 v29, v165, v45
	v_cvt_pk_bf16_f32 v27, v42, v43
	v_pk_mul_f32 v[30:31], v[158:159], v[46:47]
	v_mfma_f32_16x16x32_bf16 v[4:7], v[226:229], v[200:203], v[4:7]
	v_cvt_pk_bf16_f32 v52, v36, v37
	s_nop 1
	v_pk_mul_f32 v[18:19], v[146:147], v[18:19]
	v_pk_mul_f32 v[0:1], v[142:143], v[16:17]
	s_waitcnt lgkmcnt(3)
	v_mfma_f32_16x16x32_bf16 v[8:11], v[230:233], v[200:203], v[8:11]
	v_cvt_pk_bf16_f32 v0, v0, v1
	v_pk_mul_f32 v[6:7], v[148:149], v[6:7]
	v_pk_mul_f32 v[4:5], v[144:145], v[4:5]
	v_cvt_pk_bf16_f32 v1, v18, v19
	v_cvt_pk_bf16_f32 v4, v4, v5
	s_nop 2
	v_pk_mul_f32 v[16:17], v[146:147], v[10:11]
	v_pk_mul_f32 v[44:45], v[142:143], v[8:9]
	v_cvt_pk_bf16_f32 v5, v6, v7
	v_cvt_pk_bf16_f32 v6, v44, v45
	v_cvt_pk_bf16_f32 v7, v16, v17
	v_mfma_f32_16x16x32_bf16 v[12:15], v[48:51], v[200:203], v[188:191]
	v_cvt_pk_bf16_f32 v53, v38, v39
	v_pk_mul_f32 v[38:39], v[158:159], v[38:39]
	v_pk_mul_f32 v[36:37], v[164:165], v[36:37]
	v_mfma_f32_16x16x32_bf16 v[20:23], v[48:51], v[196:199], v[20:23]
	v_cvt_pk_bf16_f32 v54, v32, v33
	v_cvt_pk_bf16_f32 v55, v34, v35
	v_pk_mul_f32 v[42:43], v[158:159], v[42:43]
	v_mfma_f32_16x16x32_bf16 v[8:11], v[212:215], v[0:3], 0
	v_mul_f32_e64 v40, v164, v40
	v_mul_f32_e64 v41, v165, v41
	v_pk_mul_f32 v[34:35], v[158:159], v[34:35]
	v_pk_mul_f32 v[32:33], v[164:165], v[32:33]
	v_mfma_f32_16x16x32_bf16 v[4:7], v[212:215], v[4:7], 0
	v_mul_f32_e64 v50, v158, v222
	v_mul_f32_e64 v51, v159, v223
	s_nop 0
	v_pk_fma_f32 v[8:9], v[162:163], v[20:21], v[8:9]
	v_pk_mul_f32 v[48:49], v[164:165], v[220:221]
	v_cvt_pk_bf16_f32 v8, v8, v9
	v_cvt_pk_bf16_f32 v56, v220, v221
	s_nop 0
	v_pk_fma_f32 v[0:1], v[166:167], v[14:15], v[6:7]
	v_pk_fma_f32 v[6:7], v[168:169], v[22:23], v[10:11]
	v_pk_fma_f32 v[4:5], v[160:161], v[12:13], v[4:5]
	v_cvt_pk_bf16_f32 v9, v6, v7
	v_cvt_pk_bf16_f32 v4, v4, v5
	v_cvt_pk_bf16_f32 v5, v0, v1
	global_store_dwordx2 v[242:243], v[8:9], off
	global_store_dwordx2 v[234:235], v[4:5], off
	global_load_dwordx4 v[12:15], v[236:237], off
	s_nop 0
	global_load_dwordx4 v[8:11], v[238:239], off
	global_load_dwordx4 v[4:7], v[240:241], off
	s_waitcnt lgkmcnt(0)
	s_barrier
	ds_read_b64 v[16:17], v183 offset:1536
	ds_read_b64 v[18:19], v183 offset:1568
	ds_read_b64 v[20:21], v184 offset:1792
	ds_read_b64 v[22:23], v184 offset:1824
	ds_read_b64 v[60:61], v184 offset:1856
	ds_read_b64 v[62:63], v184 offset:1888
	ds_read_b64 v[44:45], v185
	ds_read_b64 v[46:47], v185 offset:32
	ds_read_b64 v[188:189], v186 offset:256
	ds_read_b64 v[190:191], v186 offset:288
	ds_read_b64_tr_b16 v[194:195], v176 offset:39168
	ds_read_b64_tr_b16 v[196:197], v177 offset:43520
	ds_read_b64_tr_b16 v[198:199], v177 offset:47872
	ds_read_b64_tr_b16 v[192:193], v176 offset:34816
	ds_read_b64_tr_b16 v[200:201], v176 offset:34848
	ds_read_b64_tr_b16 v[212:213], v176 offset:34880
	ds_read_b64_tr_b16 v[214:215], v176 offset:39232
	s_waitcnt lgkmcnt(13)
	v_mfma_f32_16x16x32_bf16 v[226:229], v[24:27], v[20:23], 0
	s_waitcnt lgkmcnt(5)
	v_lshlrev_b32_e32 v0, 16, v196
	v_and_b32_e32 v1, 0xffff0000, v196
	v_pk_mul_f32 v[0:1], v[150:151], v[0:1]
	v_mfma_f32_16x16x32_bf16 v[234:237], v[24:27], v[16:19], 0
	v_lshlrev_b32_e32 v24, 16, v197
	v_and_b32_e32 v25, 0xffff0000, v197
	v_pk_mul_f32 v[24:25], v[152:153], v[24:25]
	v_mfma_f32_16x16x32_bf16 v[238:241], v[44:47], v[16:19], 0
	s_waitcnt lgkmcnt(4)
	v_lshlrev_b32_e32 v16, 16, v198
	v_and_b32_e32 v17, 0xffff0000, v198
	v_lshlrev_b32_e32 v18, 16, v199
	v_and_b32_e32 v19, 0xffff0000, v199
	v_mfma_f32_16x16x32_bf16 v[242:245], v[44:47], v[20:23], 0
	ds_read_b64_tr_b16 v[202:203], v176 offset:39200
	ds_read_b64_tr_b16 v[230:231], v176 offset:35040
	v_cvt_pk_bf16_f32 v57, v222, v223
	v_cvt_pk_bf16_f32 v58, v216, v217
	v_mfma_f32_16x16x32_bf16 v[188:191], v[188:191], v[20:23], 0
	v_mul_f32_e64 v20, v154, v16
	v_mul_f32_e64 v21, v155, v17
	v_pk_mul_f32 v[22:23], v[156:157], v[18:19]
	v_cvt_pk_bf16_f32 v16, v0, v1
	v_cvt_pk_bf16_f32 v17, v24, v25
	v_cvt_pk_bf16_f32 v18, v20, v21
	v_cvt_pk_bf16_f32 v19, v22, v23
	ds_read_b64_tr_b16 v[22:23], v176 offset:39264
	ds_read_b64_tr_b16 v[20:21], v176 offset:34912
	ds_read_b64_tr_b16 v[24:25], v176 offset:34944
	s_waitcnt lgkmcnt(8)
	v_mfma_f32_16x16x32_bf16 v[44:47], v[192:195], v[16:19], v[28:31]
	ds_read_b64_tr_b16 v[192:193], v176 offset:34976
	ds_read_b64_tr_b16 v[26:27], v176 offset:39296
	ds_read_b64_tr_b16 v[194:195], v176 offset:39328
	ds_read_b64_tr_b16 v[232:233], v176 offset:39392
	v_cvt_pk_bf16_f32 v59, v218, v219
	s_waitcnt lgkmcnt(9)
	v_mfma_f32_16x16x32_bf16 v[36:39], v[212:215], v[16:19], v[36:39]
	ds_read_b64_tr_b16 v[212:213], v176 offset:35008
	ds_read_b64_tr_b16 v[214:215], v176 offset:39360
	s_waitcnt lgkmcnt(10)
	v_mfma_f32_16x16x32_bf16 v[40:43], v[200:203], v[16:19], v[40:43]
	v_mul_f32_e64 v202, v158, v218
	v_mul_f32_e64 v203, v159, v219
	v_pk_mul_f32 v[200:201], v[164:165], v[216:217]
	ds_read_b64 v[216:217], v183 offset:1664
	ds_read_b64 v[218:219], v183 offset:1696
	s_waitcnt lgkmcnt(9)
	v_mfma_f32_16x16x32_bf16 v[32:35], v[20:23], v[16:19], v[32:35]
	v_mul_f32_e64 v22, v158, v210
	v_mul_f32_e64 v23, v159, v211
	v_pk_mul_f32 v[20:21], v[164:165], v[208:209]
	s_waitcnt lgkmcnt(6)
	v_mfma_f32_16x16x32_bf16 v[28:31], v[24:27], v[16:19], v[48:51]
	s_waitcnt lgkmcnt(5)
	v_mfma_f32_16x16x32_bf16 v[24:27], v[192:195], v[16:19], v[200:203]
	ds_read_b64 v[192:193], v185 offset:64
	ds_read_b64 v[194:195], v185 offset:96
	v_pk_mul_f32 v[50:51], v[158:159], v[206:207]
	v_pk_mul_f32 v[48:49], v[164:165], v[204:205]
	s_waitcnt lgkmcnt(4)
	v_mfma_f32_16x16x32_bf16 v[20:23], v[212:215], v[16:19], v[20:23]
	ds_read_b64 v[212:213], v186 offset:320
	ds_read_b64 v[214:215], v186 offset:352
	v_cvt_pk_bf16_f32 v202, v204, v205
	v_cvt_pk_bf16_f32 v203, v206, v207
	v_mfma_f32_16x16x32_bf16 v[16:19], v[230:233], v[16:19], v[48:51]
	ds_read_b64 v[204:205], v183 offset:1728
	ds_read_b64 v[206:207], v183 offset:1760
	v_cvt_pk_bf16_f32 v200, v208, v209
	v_cvt_pk_bf16_f32 v201, v210, v211
	ds_read_b64 v[48:49], v183 offset:1600
	ds_read_b64 v[50:51], v183 offset:1632
	v_mfma_f32_16x16x32_bf16 v[226:229], v[52:55], v[60:63], v[226:229]
	s_waitcnt lgkmcnt(0)
	v_mfma_f32_16x16x32_bf16 v[52:55], v[52:55], v[48:51], v[234:237]
	v_mfma_f32_16x16x32_bf16 v[48:51], v[192:195], v[48:51], v[238:241]
	v_mfma_f32_16x16x32_bf16 v[192:195], v[192:195], v[60:63], v[242:245]
	v_mfma_f32_16x16x32_bf16 v[60:63], v[212:215], v[60:63], v[188:191]
	s_nop 2
	ds_read_b64 v[188:189], v184 offset:1920
	ds_read_b64 v[190:191], v184 offset:1952
	s_waitcnt lgkmcnt(0)
	v_mfma_f32_16x16x32_bf16 v[212:215], v[56:59], v[188:191], v[226:229]
	v_mfma_f32_16x16x32_bf16 v[52:55], v[56:59], v[216:219], v[52:55]
	ds_read_b64 v[56:57], v185 offset:128
	ds_read_b64 v[58:59], v185 offset:160
	s_waitcnt lgkmcnt(0)
	v_mfma_f32_16x16x32_bf16 v[48:51], v[56:59], v[216:219], v[48:51]
	v_mfma_f32_16x16x32_bf16 v[56:59], v[56:59], v[188:191], v[192:195]
	s_nop 2
	ds_read_b64 v[192:193], v186 offset:384
	ds_read_b64 v[194:195], v186 offset:416
	s_waitcnt lgkmcnt(0)
	v_mfma_f32_16x16x32_bf16 v[60:63], v[192:195], v[188:191], v[60:63]
	ds_read_b64 v[188:189], v184 offset:1984
	ds_read_b64 v[190:191], v184 offset:2016
	ds_read_b64 v[182:183], v185 offset:192
	ds_read_b64 v[184:185], v185 offset:224
	s_waitcnt lgkmcnt(0)
	v_mfma_f32_16x16x32_bf16 v[48:51], v[182:185], v[204:207], v[48:51]
	s_nop 7
	v_pk_mul_f32 v[50:51], v[146:147], v[50:51]
	v_mfma_f32_16x16x32_bf16 v[56:59], v[182:185], v[188:191], v[56:59]
	ds_read_b64 v[182:183], v186 offset:448
	ds_read_b64 v[184:185], v186 offset:480
	v_pk_mul_f32 v[0:1], v[142:143], v[48:49]
	s_waitcnt lgkmcnt(0)
	v_mfma_f32_16x16x32_bf16 v[60:63], v[182:185], v[188:191], v[60:63]
	s_nop 3
	v_mul_f32_e64 v182, v148, v58
	v_mul_f32_e64 v183, v149, v59
	v_pk_mul_f32 v[48:49], v[144:145], v[56:57]
	v_cvt_pk_bf16_f32 v0, v0, v1
	v_pk_mul_f32 v[62:63], v[146:147], v[62:63]
	v_pk_mul_f32 v[60:61], v[142:143], v[60:61]
	v_cvt_pk_bf16_f32 v1, v50, v51
	v_cvt_pk_bf16_f32 v48, v48, v49
	v_cvt_pk_bf16_f32 v49, v182, v183
	v_cvt_pk_bf16_f32 v50, v60, v61
	v_cvt_pk_bf16_f32 v51, v62, v63
	v_mfma_f32_16x16x32_bf16 v[192:195], v[200:203], v[188:191], v[212:215]
	v_mfma_f32_16x16x32_bf16 v[52:55], v[200:203], v[204:207], v[52:55]
	v_lshl_add_u64 v[200:201], v[170:171], 0, v[246:247]
	v_lshl_add_u64 v[202:203], v[170:171], 0, v[248:249]
	v_mfma_f32_16x16x32_bf16 v[56:59], v[196:199], v[0:3], 0
	v_mfma_f32_16x16x32_bf16 v[48:51], v[196:199], v[48:51], 0
	s_nop 6
	v_fma_f32 v52, v162, v52, v56
	v_fma_f32 v53, v163, v53, v57
	v_pk_fma_f32 v[0:1], v[166:167], v[194:195], v[50:51]
	v_pk_fma_f32 v[50:51], v[168:169], v[54:55], v[58:59]
	v_pk_fma_f32 v[48:49], v[160:161], v[192:193], v[48:49]
	v_cvt_pk_bf16_f32 v52, v52, v53
	v_cvt_pk_bf16_f32 v53, v50, v51
	v_cvt_pk_bf16_f32 v48, v48, v49
	v_cvt_pk_bf16_f32 v49, v0, v1
	global_store_dwordx2 v[200:201], v[52:53], off
	global_store_dwordx2 v[202:203], v[48:49], off
	s_cbranch_scc0 .LBB0_1370
	s_andn2_b64 vcc, exec, s[6:7]
	s_cbranch_vccnz .LBB0_1354
	s_add_u32 s0, s28, s14
	s_addc_u32 s1, s29, s15
	v_lshl_add_u64 v[0:1], v[112:113], 2, s[0:1]
	s_waitcnt vmcnt(2)
	v_lshl_add_u64 v[4:5], v[0:1], 0, v[76:77]
	global_store_dword v[4:5], v44, off nt
	v_lshl_add_u64 v[4:5], v[0:1], 0, v[78:79]
	global_store_dword v[4:5], v45, off nt
	v_lshl_add_u64 v[4:5], v[0:1], 0, v[80:81]
	global_store_dword v[4:5], v46, off nt
	v_lshl_add_u64 v[4:5], v[0:1], 0, v[82:83]
	global_store_dword v[4:5], v47, off nt
	v_lshl_add_u64 v[4:5], v[0:1], 0, v[84:85]
	global_store_dword v[4:5], v40, off nt
	v_lshl_add_u64 v[4:5], v[0:1], 0, v[86:87]
	global_store_dword v[4:5], v41, off nt
	v_lshl_add_u64 v[4:5], v[0:1], 0, v[88:89]
	global_store_dword v[4:5], v42, off nt
	v_lshl_add_u64 v[4:5], v[0:1], 0, v[90:91]
	global_store_dword v[4:5], v43, off nt
	v_lshl_add_u64 v[4:5], v[0:1], 0, v[92:93]
	global_store_dword v[4:5], v36, off nt
	v_lshl_add_u64 v[4:5], v[0:1], 0, v[94:95]
	global_store_dword v[4:5], v37, off nt
	v_lshl_add_u64 v[4:5], v[0:1], 0, v[96:97]
	global_store_dword v[4:5], v38, off nt
	v_lshl_add_u64 v[4:5], v[0:1], 0, v[98:99]
	global_store_dword v[4:5], v39, off nt
	v_lshl_add_u64 v[4:5], v[0:1], 0, v[100:101]
	global_store_dword v[4:5], v32, off nt
	v_lshl_add_u64 v[4:5], v[0:1], 0, v[102:103]
	global_store_dword v[4:5], v33, off nt
	v_lshl_add_u64 v[4:5], v[0:1], 0, v[104:105]
	global_store_dword v[4:5], v34, off nt
	v_lshl_add_u64 v[4:5], v[0:1], 0, v[106:107]
	global_store_dword v[4:5], v35, off nt
	v_lshl_add_u64 v[4:5], v[0:1], 0, v[108:109]
	global_store_dword v[4:5], v28, off nt
	v_lshl_add_u64 v[4:5], v[0:1], 0, v[110:111]
	global_store_dword v[4:5], v29, off nt
	v_lshl_add_u64 v[4:5], v[0:1], 0, v[138:139]
	global_store_dword v[4:5], v30, off nt
	v_lshl_add_u64 v[4:5], v[0:1], 0, v[136:137]
	global_store_dword v[4:5], v31, off nt
	v_lshl_add_u64 v[4:5], v[0:1], 0, v[134:135]
	global_store_dword v[4:5], v24, off nt
	v_lshl_add_u64 v[4:5], v[0:1], 0, v[132:133]
	global_store_dword v[4:5], v25, off nt
	v_lshl_add_u64 v[4:5], v[0:1], 0, v[130:131]
	global_store_dword v[4:5], v26, off nt
	v_lshl_add_u64 v[4:5], v[0:1], 0, v[128:129]
	global_store_dword v[4:5], v27, off nt
	v_lshl_add_u64 v[4:5], v[0:1], 0, v[126:127]
	global_store_dword v[4:5], v20, off nt
	v_lshl_add_u64 v[4:5], v[0:1], 0, v[124:125]
	global_store_dword v[4:5], v21, off nt
	v_lshl_add_u64 v[4:5], v[0:1], 0, v[122:123]
	global_store_dword v[4:5], v22, off nt
	v_lshl_add_u64 v[4:5], v[0:1], 0, v[120:121]
	global_store_dword v[4:5], v23, off nt
	v_lshl_add_u64 v[4:5], v[0:1], 0, v[118:119]
	global_store_dword v[4:5], v16, off nt
	v_lshl_add_u64 v[4:5], v[0:1], 0, v[116:117]
	global_store_dword v[4:5], v17, off nt
	v_lshl_add_u64 v[4:5], v[0:1], 0, v[114:115]
	v_lshl_add_u64 v[0:1], v[0:1], 0, v[140:141]
	global_store_dword v[4:5], v18, off nt
	global_store_dword v[0:1], v19, off nt
	s_branch .LBB0_1354
